# resid epilogue regenerated: all XB loads hoisted with counted vmcnt, saddr addressing, packed square-sum, shuffles batched at the end
# speedup vs baseline: 1.0128x; 1.0022x over previous
; __device__ __forceinline__ unsigned pk2(float lo, float hi) { f32x2 v = {lo, hi}; bf16x2_t b = __builtin_convertvector(v, bf16x2_t); return __builtin_bit_cast(unsigned, b); }
; __device__ __forceinline__ f32x4 bf_lo4(const u32x4& w) { return (f32x4){__uint_as_float(w[0] << 16), __uint_as_float(w[0] & 0xffff0000u), __uint_as_float(w[1] << 16), __uint_as_float(w[1] & 0xffff0000u)}; }
; __device__ __forceinline__ f32x4 bf_hi4(const u32x4& w) { return (f32x4){__uint_as_float(w[2] << 16), __uint_as_float(w[2] & 0xffff0000u), __uint_as_float(w[3] << 16), __uint_as_float(w[3] & 0xffff0000u)}; }
; __device__ __forceinline__ void epi_resid(bf16_t* XB, float* SS, float alpha, const f32x4 (&acc)[2][2][4][2], const Unit& u, int wr, int wc, int fr, int fq) {
;     const int c0 = u.pn * 256 + wc * 32 + fq * 8;
;     u32x4 pre[2][2];
;     { const bf16_t* p = XB + (size_t)opaque(EPI_ROW(0)) * DM + c0; pre[0][0] = *(const u32x4*)p; pre[0][1] = *(const u32x4*)(p + 128); }
; #pragma unroll
;     for (int it = 0; it < 8; ++it) {
;         const int ai = it >> 2, m = it & 3; const int r = opaque(EPI_ROW(it));
;         if (it + 1 < 8) { const bf16_t* p = XB + (size_t)opaque(EPI_ROW(it + 1)) * DM + c0; pre[(it + 1) & 1][0] = *(const u32x4*)p; pre[(it + 1) & 1][1] = *(const u32x4*)(p + 128); }
;         float q = 0.f;
; #pragma unroll
;         for (int bj = 0; bj < 2; ++bj) {
;             const size_t off = (size_t)r * DM + c0 + bj * 128;
;             const u32x4 bw = pre[it & 1][bj];
;             const f32x4 o0 = bf_lo4(bw) + acc[ai][bj][m][0] * alpha, o1 = bf_hi4(bw) + acc[ai][bj][m][1] * alpha;
;             u32x4 w; w[0] = pk2(o0[0], o0[1]); w[1] = pk2(o0[2], o0[3]); w[2] = pk2(o1[0], o1[1]); w[3] = pk2(o1[2], o1[3]);
;             *(u32x4*)(XB + off) = w;
;             q += (o0[0] * o0[0] + o0[1] * o0[1]) + (o0[2] * o0[2] + o0[3] * o0[3]) + (o1[0] * o1[0] + o1[1] * o1[1]) + (o1[2] * o1[2] + o1[3] * o1[3]);
.LBB0_733:
	s_andn2_b64 vcc, exec, s[2:3]
	s_cbranch_vccnz .LBB0_754
	s_cmp_gt_i32 s88, 0
	s_mov_b64 s[2:3], -1
	s_cbranch_scc0 .LBB0_752
	s_mov_b64 s[2:3], s[96:97]
	s_add_u32 s12, s2, 0x13800000
	s_addc_u32 s13, s3, 0
	s_add_u32 s2, s2, 0x17800000
	s_addc_u32 s3, s3, 0
	s_lshl_b32 s14, s81, 8
	s_waitcnt lgkmcnt(0)
	v_add_u32_e32 v130, s14, v193
	v_lshl_or_b32 v131, s77, 8, v194
	v_lshlrev_b32_e32 v180, 7, v130
	v_lshlrev_b32_e32 v130, 12, v130
	v_lshl_add_u32 v130, v131, 1, v130
	v_readlane_b32 s18, v254, 30
	s_lshl_b32 s16, s77, 4
	s_lshl_b32 s18, s18, 2
	s_add_i32 s16, s16, s18
	s_addk_i32 s16, 0x1000
	v_add_u32_e32 v180, s16, v180
	v_add_u32_e32 v181, 0x4000, v180
	v_xor_b32_e32 v214, 16, v228
	v_xor_b32_e32 v215, 32, v228
	v_lshlrev_b32_e32 v214, 2, v214
	v_lshlrev_b32_e32 v215, 2, v215
	global_load_dwordx4 v[132:135], v130, s[12:13]
	global_load_dwordx4 v[136:139], v130, s[12:13] offset:256
	v_add_u32_e32 v131, 0x10000, v130
	global_load_dwordx4 v[140:143], v131, s[12:13]
	global_load_dwordx4 v[144:147], v131, s[12:13] offset:256
	v_add_u32_e32 v131, 0x20000, v130
	global_load_dwordx4 v[148:151], v131, s[12:13]
	global_load_dwordx4 v[152:155], v131, s[12:13] offset:256
	v_add_u32_e32 v131, 0x30000, v130
	global_load_dwordx4 v[156:159], v131, s[12:13]
	global_load_dwordx4 v[160:163], v131, s[12:13] offset:256
	v_add_u32_e32 v131, 0x80000, v130
	global_load_dwordx4 v[164:167], v131, s[12:13]
	global_load_dwordx4 v[168:171], v131, s[12:13] offset:256
	v_add_u32_e32 v131, 0x90000, v130
	global_load_dwordx4 v[172:175], v131, s[12:13]
	global_load_dwordx4 v[176:179], v131, s[12:13] offset:256
	s_waitcnt vmcnt(10)
	v_lshlrev_b32_e32 v200, 16, v132
	v_and_b32_e32 v201, 0xffff0000, v132
	v_lshlrev_b32_e32 v202, 16, v133
	v_and_b32_e32 v203, 0xffff0000, v133
	v_lshlrev_b32_e32 v204, 16, v134
	v_and_b32_e32 v205, 0xffff0000, v134
	v_lshlrev_b32_e32 v206, 16, v135
	v_and_b32_e32 v207, 0xffff0000, v135
	v_pk_fma_f32 v[126:127], v[126:127], s[40:41], v[200:201]
	v_pk_fma_f32 v[128:129], v[128:129], s[40:41], v[202:203]
	v_pk_fma_f32 v[118:119], v[118:119], s[40:41], v[204:205]
	v_pk_fma_f32 v[120:121], v[120:121], s[40:41], v[206:207]
	v_cvt_pk_bf16_f32 v132, v126, v127
	v_cvt_pk_bf16_f32 v133, v128, v129
	v_cvt_pk_bf16_f32 v134, v118, v119
	v_cvt_pk_bf16_f32 v135, v120, v121
	v_pk_mul_f32 v[208:209], v[126:127], v[126:127]
	v_pk_fma_f32 v[208:209], v[128:129], v[128:129], v[208:209]
	v_pk_fma_f32 v[208:209], v[118:119], v[118:119], v[208:209]
	v_pk_fma_f32 v[208:209], v[120:121], v[120:121], v[208:209]
	global_store_dwordx4 v130, v[132:135], s[12:13]
	v_lshlrev_b32_e32 v200, 16, v136
	v_and_b32_e32 v201, 0xffff0000, v136
	v_lshlrev_b32_e32 v202, 16, v137
	v_and_b32_e32 v203, 0xffff0000, v137
	v_lshlrev_b32_e32 v204, 16, v138
	v_and_b32_e32 v205, 0xffff0000, v138
	v_lshlrev_b32_e32 v206, 16, v139
	v_and_b32_e32 v207, 0xffff0000, v139
	v_pk_fma_f32 v[122:123], v[122:123], s[40:41], v[200:201]
	v_pk_fma_f32 v[124:125], v[124:125], s[40:41], v[202:203]
	v_pk_fma_f32 v[114:115], v[114:115], s[40:41], v[204:205]
	v_pk_fma_f32 v[116:117], v[116:117], s[40:41], v[206:207]
	v_cvt_pk_bf16_f32 v136, v122, v123
	v_cvt_pk_bf16_f32 v137, v124, v125
	v_cvt_pk_bf16_f32 v138, v114, v115
	v_cvt_pk_bf16_f32 v139, v116, v117
	v_pk_fma_f32 v[208:209], v[122:123], v[122:123], v[208:209]
	v_pk_fma_f32 v[208:209], v[124:125], v[124:125], v[208:209]
	v_pk_fma_f32 v[208:209], v[114:115], v[114:115], v[208:209]
	v_pk_fma_f32 v[208:209], v[116:117], v[116:117], v[208:209]
	global_store_dwordx4 v130, v[136:139], s[12:13] offset:256
	v_add_f32_e32 v244, v208, v209
	v_add_u32_e32 v131, 0xa0000, v130
	global_load_dwordx4 v[126:129], v131, s[12:13]
	global_load_dwordx4 v[122:125], v131, s[12:13] offset:256
	v_add_u32_e32 v131, 0xb0000, v130
	global_load_dwordx4 v[118:121], v131, s[12:13]
	global_load_dwordx4 v[114:117], v131, s[12:13] offset:256
	s_waitcnt vmcnt(14)
	v_lshlrev_b32_e32 v200, 16, v140
	v_and_b32_e32 v201, 0xffff0000, v140
	v_lshlrev_b32_e32 v202, 16, v141
	v_and_b32_e32 v203, 0xffff0000, v141
	v_lshlrev_b32_e32 v204, 16, v142
	v_and_b32_e32 v205, 0xffff0000, v142
	v_lshlrev_b32_e32 v206, 16, v143
	v_and_b32_e32 v207, 0xffff0000, v143
	v_pk_fma_f32 v[110:111], v[110:111], s[40:41], v[200:201]
	v_pk_fma_f32 v[112:113], v[112:113], s[40:41], v[202:203]
	v_pk_fma_f32 v[102:103], v[102:103], s[40:41], v[204:205]
	v_pk_fma_f32 v[104:105], v[104:105], s[40:41], v[206:207]
	v_cvt_pk_bf16_f32 v140, v110, v111
	v_cvt_pk_bf16_f32 v141, v112, v113
	v_cvt_pk_bf16_f32 v142, v102, v103
	v_cvt_pk_bf16_f32 v143, v104, v105
	v_pk_mul_f32 v[208:209], v[110:111], v[110:111]
	v_pk_fma_f32 v[208:209], v[112:113], v[112:113], v[208:209]
	v_pk_fma_f32 v[208:209], v[102:103], v[102:103], v[208:209]
	v_pk_fma_f32 v[208:209], v[104:105], v[104:105], v[208:209]
	v_add_u32_e32 v131, 0x10000, v130
	global_store_dwordx4 v131, v[140:143], s[12:13]
	v_lshlrev_b32_e32 v200, 16, v144
	v_and_b32_e32 v201, 0xffff0000, v144
	v_lshlrev_b32_e32 v202, 16, v145
	v_and_b32_e32 v203, 0xffff0000, v145
	v_lshlrev_b32_e32 v204, 16, v146
	v_and_b32_e32 v205, 0xffff0000, v146
	v_lshlrev_b32_e32 v206, 16, v147
	v_and_b32_e32 v207, 0xffff0000, v147
	v_pk_fma_f32 v[106:107], v[106:107], s[40:41], v[200:201]
	v_pk_fma_f32 v[108:109], v[108:109], s[40:41], v[202:203]
	v_pk_fma_f32 v[98:99], v[98:99], s[40:41], v[204:205]
	v_pk_fma_f32 v[100:101], v[100:101], s[40:41], v[206:207]
	v_cvt_pk_bf16_f32 v144, v106, v107
	v_cvt_pk_bf16_f32 v145, v108, v109
	v_cvt_pk_bf16_f32 v146, v98, v99
	v_cvt_pk_bf16_f32 v147, v100, v101
	v_pk_fma_f32 v[208:209], v[106:107], v[106:107], v[208:209]
	v_pk_fma_f32 v[208:209], v[108:109], v[108:109], v[208:209]
	v_pk_fma_f32 v[208:209], v[98:99], v[98:99], v[208:209]
	v_pk_fma_f32 v[208:209], v[100:101], v[100:101], v[208:209]
	global_store_dwordx4 v131, v[144:147], s[12:13] offset:256
	v_add_f32_e32 v245, v208, v209
	s_waitcnt vmcnt(14)
; __device__ __forceinline__ unsigned pk2(float lo, float hi) { f32x2 v = {lo, hi}; bf16x2_t b = __builtin_convertvector(v, bf16x2_t); return __builtin_bit_cast(unsigned, b); }
; __device__ __forceinline__ f32x4 bf_lo4(const u32x4& w) { return (f32x4){__uint_as_float(w[0] << 16), __uint_as_float(w[0] & 0xffff0000u), __uint_as_float(w[1] << 16), __uint_as_float(w[1] & 0xffff0000u)}; }
; __device__ __forceinline__ f32x4 bf_hi4(const u32x4& w) { return (f32x4){__uint_as_float(w[2] << 16), __uint_as_float(w[2] & 0xffff0000u), __uint_as_float(w[3] << 16), __uint_as_float(w[3] & 0xffff0000u)}; }
; __device__ __forceinline__ void epi_resid(bf16_t* XB, float* SS, float alpha, const f32x4 (&acc)[2][2][4][2], const Unit& u, int wr, int wc, int fr, int fq) {
;     ...
;     for (int it = 0; it < 8; ++it) {
;         const int ai = it >> 2, m = it & 3; const int r = opaque(EPI_ROW(it));
;         if (it + 1 < 8) { const bf16_t* p = XB + (size_t)opaque(EPI_ROW(it + 1)) * DM + c0; pre[(it + 1) & 1][0] = *(const u32x4*)p; pre[(it + 1) & 1][1] = *(const u32x4*)(p + 128); }
;         float q = 0.f;
; #pragma unroll
;         for (int bj = 0; bj < 2; ++bj) {
;             const size_t off = (size_t)r * DM + c0 + bj * 128;
;             const u32x4 bw = pre[it & 1][bj];
;             const f32x4 o0 = bf_lo4(bw) + acc[ai][bj][m][0] * alpha, o1 = bf_hi4(bw) + acc[ai][bj][m][1] * alpha;
;             u32x4 w; w[0] = pk2(o0[0], o0[1]); w[1] = pk2(o0[2], o0[3]); w[2] = pk2(o1[0], o1[1]); w[3] = pk2(o1[2], o1[3]);
;             *(u32x4*)(XB + off) = w;
;             q += (o0[0] * o0[0] + o0[1] * o0[1]) + (o0[2] * o0[2] + o0[3] * o0[3]) + (o1[0] * o1[0] + o1[1] * o1[1]) + (o1[2] * o1[2] + o1[3] * o1[3]);
	v_lshlrev_b32_e32 v200, 16, v148
	v_and_b32_e32 v201, 0xffff0000, v148
	v_lshlrev_b32_e32 v202, 16, v149
	v_and_b32_e32 v203, 0xffff0000, v149
	v_lshlrev_b32_e32 v204, 16, v150
	v_and_b32_e32 v205, 0xffff0000, v150
	v_lshlrev_b32_e32 v206, 16, v151
	v_and_b32_e32 v207, 0xffff0000, v151
	v_pk_fma_f32 v[94:95], v[94:95], s[40:41], v[200:201]
	v_pk_fma_f32 v[96:97], v[96:97], s[40:41], v[202:203]
	v_pk_fma_f32 v[86:87], v[86:87], s[40:41], v[204:205]
	v_pk_fma_f32 v[88:89], v[88:89], s[40:41], v[206:207]
	v_cvt_pk_bf16_f32 v148, v94, v95
	v_cvt_pk_bf16_f32 v149, v96, v97
	v_cvt_pk_bf16_f32 v150, v86, v87
	v_cvt_pk_bf16_f32 v151, v88, v89
	v_pk_mul_f32 v[208:209], v[94:95], v[94:95]
	v_pk_fma_f32 v[208:209], v[96:97], v[96:97], v[208:209]
	v_pk_fma_f32 v[208:209], v[86:87], v[86:87], v[208:209]
	v_pk_fma_f32 v[208:209], v[88:89], v[88:89], v[208:209]
	v_add_u32_e32 v131, 0x20000, v130
	global_store_dwordx4 v131, v[148:151], s[12:13]
	v_lshlrev_b32_e32 v200, 16, v152
	v_and_b32_e32 v201, 0xffff0000, v152
	v_lshlrev_b32_e32 v202, 16, v153
	v_and_b32_e32 v203, 0xffff0000, v153
	v_lshlrev_b32_e32 v204, 16, v154
	v_and_b32_e32 v205, 0xffff0000, v154
	v_lshlrev_b32_e32 v206, 16, v155
	v_and_b32_e32 v207, 0xffff0000, v155
	v_pk_fma_f32 v[90:91], v[90:91], s[40:41], v[200:201]
	v_pk_fma_f32 v[92:93], v[92:93], s[40:41], v[202:203]
	v_pk_fma_f32 v[82:83], v[82:83], s[40:41], v[204:205]
	v_pk_fma_f32 v[84:85], v[84:85], s[40:41], v[206:207]
	v_cvt_pk_bf16_f32 v152, v90, v91
	v_cvt_pk_bf16_f32 v153, v92, v93
	v_cvt_pk_bf16_f32 v154, v82, v83
	v_cvt_pk_bf16_f32 v155, v84, v85
	v_pk_fma_f32 v[208:209], v[90:91], v[90:91], v[208:209]
	v_pk_fma_f32 v[208:209], v[92:93], v[92:93], v[208:209]
	v_pk_fma_f32 v[208:209], v[82:83], v[82:83], v[208:209]
	v_pk_fma_f32 v[208:209], v[84:85], v[84:85], v[208:209]
	global_store_dwordx4 v131, v[152:155], s[12:13] offset:256
	v_add_f32_e32 v246, v208, v209
	s_waitcnt vmcnt(14)
	v_lshlrev_b32_e32 v200, 16, v156
	v_and_b32_e32 v201, 0xffff0000, v156
	v_lshlrev_b32_e32 v202, 16, v157
	v_and_b32_e32 v203, 0xffff0000, v157
	v_lshlrev_b32_e32 v204, 16, v158
	v_and_b32_e32 v205, 0xffff0000, v158
	v_lshlrev_b32_e32 v206, 16, v159
	v_and_b32_e32 v207, 0xffff0000, v159
	v_pk_fma_f32 v[78:79], v[78:79], s[40:41], v[200:201]
	v_pk_fma_f32 v[80:81], v[80:81], s[40:41], v[202:203]
	v_pk_fma_f32 v[70:71], v[70:71], s[40:41], v[204:205]
	v_pk_fma_f32 v[72:73], v[72:73], s[40:41], v[206:207]
	v_cvt_pk_bf16_f32 v156, v78, v79
	v_cvt_pk_bf16_f32 v157, v80, v81
	v_cvt_pk_bf16_f32 v158, v70, v71
	v_cvt_pk_bf16_f32 v159, v72, v73
	v_pk_mul_f32 v[208:209], v[78:79], v[78:79]
	v_pk_fma_f32 v[208:209], v[80:81], v[80:81], v[208:209]
	v_pk_fma_f32 v[208:209], v[70:71], v[70:71], v[208:209]
	v_pk_fma_f32 v[208:209], v[72:73], v[72:73], v[208:209]
	v_add_u32_e32 v131, 0x30000, v130
	global_store_dwordx4 v131, v[156:159], s[12:13]
	v_lshlrev_b32_e32 v200, 16, v160
	v_and_b32_e32 v201, 0xffff0000, v160
	v_lshlrev_b32_e32 v202, 16, v161
	v_and_b32_e32 v203, 0xffff0000, v161
	v_lshlrev_b32_e32 v204, 16, v162
	v_and_b32_e32 v205, 0xffff0000, v162
	v_lshlrev_b32_e32 v206, 16, v163
	v_and_b32_e32 v207, 0xffff0000, v163
	v_pk_fma_f32 v[74:75], v[74:75], s[40:41], v[200:201]
	v_pk_fma_f32 v[76:77], v[76:77], s[40:41], v[202:203]
	v_pk_fma_f32 v[66:67], v[66:67], s[40:41], v[204:205]
	v_pk_fma_f32 v[68:69], v[68:69], s[40:41], v[206:207]
	v_cvt_pk_bf16_f32 v160, v74, v75
	v_cvt_pk_bf16_f32 v161, v76, v77
	v_cvt_pk_bf16_f32 v162, v66, v67
	v_cvt_pk_bf16_f32 v163, v68, v69
	v_pk_fma_f32 v[208:209], v[74:75], v[74:75], v[208:209]
	v_pk_fma_f32 v[208:209], v[76:77], v[76:77], v[208:209]
	v_pk_fma_f32 v[208:209], v[66:67], v[66:67], v[208:209]
	v_pk_fma_f32 v[208:209], v[68:69], v[68:69], v[208:209]
	global_store_dwordx4 v131, v[160:163], s[12:13] offset:256
	v_add_f32_e32 v247, v208, v209
	s_waitcnt vmcnt(14)
	v_lshlrev_b32_e32 v200, 16, v164
	v_and_b32_e32 v201, 0xffff0000, v164
	v_lshlrev_b32_e32 v202, 16, v165
	v_and_b32_e32 v203, 0xffff0000, v165
	v_lshlrev_b32_e32 v204, 16, v166
	v_and_b32_e32 v205, 0xffff0000, v166
	v_lshlrev_b32_e32 v206, 16, v167
	v_and_b32_e32 v207, 0xffff0000, v167
	v_pk_fma_f32 v[62:63], v[62:63], s[40:41], v[200:201]
	v_pk_fma_f32 v[64:65], v[64:65], s[40:41], v[202:203]
	v_pk_fma_f32 v[54:55], v[54:55], s[40:41], v[204:205]
	v_pk_fma_f32 v[56:57], v[56:57], s[40:41], v[206:207]
	v_cvt_pk_bf16_f32 v164, v62, v63
	v_cvt_pk_bf16_f32 v165, v64, v65
	v_cvt_pk_bf16_f32 v166, v54, v55
	v_cvt_pk_bf16_f32 v167, v56, v57
	v_pk_mul_f32 v[208:209], v[62:63], v[62:63]
	v_pk_fma_f32 v[208:209], v[64:65], v[64:65], v[208:209]
	v_pk_fma_f32 v[208:209], v[54:55], v[54:55], v[208:209]
	v_pk_fma_f32 v[208:209], v[56:57], v[56:57], v[208:209]
	v_add_u32_e32 v131, 0x80000, v130
	global_store_dwordx4 v131, v[164:167], s[12:13]
	v_lshlrev_b32_e32 v200, 16, v168
	v_and_b32_e32 v201, 0xffff0000, v168
	v_lshlrev_b32_e32 v202, 16, v169
	v_and_b32_e32 v203, 0xffff0000, v169
	v_lshlrev_b32_e32 v204, 16, v170
	v_and_b32_e32 v205, 0xffff0000, v170
	v_lshlrev_b32_e32 v206, 16, v171
	v_and_b32_e32 v207, 0xffff0000, v171
	v_pk_fma_f32 v[58:59], v[58:59], s[40:41], v[200:201]
	v_pk_fma_f32 v[60:61], v[60:61], s[40:41], v[202:203]
	v_pk_fma_f32 v[50:51], v[50:51], s[40:41], v[204:205]
	v_pk_fma_f32 v[52:53], v[52:53], s[40:41], v[206:207]
	v_cvt_pk_bf16_f32 v168, v58, v59
	v_cvt_pk_bf16_f32 v169, v60, v61
	v_cvt_pk_bf16_f32 v170, v50, v51
	v_cvt_pk_bf16_f32 v171, v52, v53
	v_pk_fma_f32 v[208:209], v[58:59], v[58:59], v[208:209]
	v_pk_fma_f32 v[208:209], v[60:61], v[60:61], v[208:209]
	v_pk_fma_f32 v[208:209], v[50:51], v[50:51], v[208:209]
	v_pk_fma_f32 v[208:209], v[52:53], v[52:53], v[208:209]
	global_store_dwordx4 v131, v[168:171], s[12:13] offset:256
	v_add_f32_e32 v210, v208, v209
	s_waitcnt vmcnt(14)
; __device__ __forceinline__ unsigned pk2(float lo, float hi) { f32x2 v = {lo, hi}; bf16x2_t b = __builtin_convertvector(v, bf16x2_t); return __builtin_bit_cast(unsigned, b); }
; __device__ __forceinline__ f32x4 bf_lo4(const u32x4& w) { return (f32x4){__uint_as_float(w[0] << 16), __uint_as_float(w[0] & 0xffff0000u), __uint_as_float(w[1] << 16), __uint_as_float(w[1] & 0xffff0000u)}; }
; __device__ __forceinline__ f32x4 bf_hi4(const u32x4& w) { return (f32x4){__uint_as_float(w[2] << 16), __uint_as_float(w[2] & 0xffff0000u), __uint_as_float(w[3] << 16), __uint_as_float(w[3] & 0xffff0000u)}; }
; __device__ __forceinline__ void epi_resid(bf16_t* XB, float* SS, float alpha, const f32x4 (&acc)[2][2][4][2], const Unit& u, int wr, int wc, int fr, int fq) {
;     ...
;     for (int it = 0; it < 8; ++it) {
;         const int ai = it >> 2, m = it & 3; const int r = opaque(EPI_ROW(it));
;         if (it + 1 < 8) { const bf16_t* p = XB + (size_t)opaque(EPI_ROW(it + 1)) * DM + c0; pre[(it + 1) & 1][0] = *(const u32x4*)p; pre[(it + 1) & 1][1] = *(const u32x4*)(p + 128); }
;         float q = 0.f;
; #pragma unroll
;         for (int bj = 0; bj < 2; ++bj) {
;             const size_t off = (size_t)r * DM + c0 + bj * 128;
;             const u32x4 bw = pre[it & 1][bj];
;             const f32x4 o0 = bf_lo4(bw) + acc[ai][bj][m][0] * alpha, o1 = bf_hi4(bw) + acc[ai][bj][m][1] * alpha;
;             u32x4 w; w[0] = pk2(o0[0], o0[1]); w[1] = pk2(o0[2], o0[3]); w[2] = pk2(o1[0], o1[1]); w[3] = pk2(o1[2], o1[3]);
;             *(u32x4*)(XB + off) = w;
;             q += (o0[0] * o0[0] + o0[1] * o0[1]) + (o0[2] * o0[2] + o0[3] * o0[3]) + (o1[0] * o1[0] + o1[1] * o1[1]) + (o1[2] * o1[2] + o1[3] * o1[3]);
	v_lshlrev_b32_e32 v200, 16, v172
	v_and_b32_e32 v201, 0xffff0000, v172
	v_lshlrev_b32_e32 v202, 16, v173
	v_and_b32_e32 v203, 0xffff0000, v173
	v_lshlrev_b32_e32 v204, 16, v174
	v_and_b32_e32 v205, 0xffff0000, v174
	v_lshlrev_b32_e32 v206, 16, v175
	v_and_b32_e32 v207, 0xffff0000, v175
	v_pk_fma_f32 v[46:47], v[46:47], s[40:41], v[200:201]
	v_pk_fma_f32 v[48:49], v[48:49], s[40:41], v[202:203]
	v_pk_fma_f32 v[38:39], v[38:39], s[40:41], v[204:205]
	v_pk_fma_f32 v[40:41], v[40:41], s[40:41], v[206:207]
	v_cvt_pk_bf16_f32 v172, v46, v47
	v_cvt_pk_bf16_f32 v173, v48, v49
	v_cvt_pk_bf16_f32 v174, v38, v39
	v_cvt_pk_bf16_f32 v175, v40, v41
	v_pk_mul_f32 v[208:209], v[46:47], v[46:47]
	v_pk_fma_f32 v[208:209], v[48:49], v[48:49], v[208:209]
	v_pk_fma_f32 v[208:209], v[38:39], v[38:39], v[208:209]
	v_pk_fma_f32 v[208:209], v[40:41], v[40:41], v[208:209]
	v_add_u32_e32 v131, 0x90000, v130
	global_store_dwordx4 v131, v[172:175], s[12:13]
	v_lshlrev_b32_e32 v200, 16, v176
	v_and_b32_e32 v201, 0xffff0000, v176
	v_lshlrev_b32_e32 v202, 16, v177
	v_and_b32_e32 v203, 0xffff0000, v177
	v_lshlrev_b32_e32 v204, 16, v178
	v_and_b32_e32 v205, 0xffff0000, v178
	v_lshlrev_b32_e32 v206, 16, v179
	v_and_b32_e32 v207, 0xffff0000, v179
	v_pk_fma_f32 v[42:43], v[42:43], s[40:41], v[200:201]
	v_pk_fma_f32 v[44:45], v[44:45], s[40:41], v[202:203]
	v_pk_fma_f32 v[34:35], v[34:35], s[40:41], v[204:205]
	v_pk_fma_f32 v[36:37], v[36:37], s[40:41], v[206:207]
	v_cvt_pk_bf16_f32 v176, v42, v43
	v_cvt_pk_bf16_f32 v177, v44, v45
	v_cvt_pk_bf16_f32 v178, v34, v35
	v_cvt_pk_bf16_f32 v179, v36, v37
	v_pk_fma_f32 v[208:209], v[42:43], v[42:43], v[208:209]
	v_pk_fma_f32 v[208:209], v[44:45], v[44:45], v[208:209]
	v_pk_fma_f32 v[208:209], v[34:35], v[34:35], v[208:209]
	v_pk_fma_f32 v[208:209], v[36:37], v[36:37], v[208:209]
	global_store_dwordx4 v131, v[176:179], s[12:13] offset:256
	v_add_f32_e32 v211, v208, v209
	s_waitcnt vmcnt(12)
	v_lshlrev_b32_e32 v200, 16, v126
	v_and_b32_e32 v201, 0xffff0000, v126
	v_lshlrev_b32_e32 v202, 16, v127
	v_and_b32_e32 v203, 0xffff0000, v127
	v_lshlrev_b32_e32 v204, 16, v128
	v_and_b32_e32 v205, 0xffff0000, v128
	v_lshlrev_b32_e32 v206, 16, v129
	v_and_b32_e32 v207, 0xffff0000, v129
	v_pk_fma_f32 v[30:31], v[30:31], s[40:41], v[200:201]
	v_pk_fma_f32 v[32:33], v[32:33], s[40:41], v[202:203]
	v_pk_fma_f32 v[22:23], v[22:23], s[40:41], v[204:205]
	v_pk_fma_f32 v[24:25], v[24:25], s[40:41], v[206:207]
	v_cvt_pk_bf16_f32 v126, v30, v31
	v_cvt_pk_bf16_f32 v127, v32, v33
	v_cvt_pk_bf16_f32 v128, v22, v23
	v_cvt_pk_bf16_f32 v129, v24, v25
	v_pk_mul_f32 v[208:209], v[30:31], v[30:31]
	v_pk_fma_f32 v[208:209], v[32:33], v[32:33], v[208:209]
	v_pk_fma_f32 v[208:209], v[22:23], v[22:23], v[208:209]
	v_pk_fma_f32 v[208:209], v[24:25], v[24:25], v[208:209]
	v_add_u32_e32 v131, 0xa0000, v130
	global_store_dwordx4 v131, v[126:129], s[12:13]
	v_lshlrev_b32_e32 v200, 16, v122
	v_and_b32_e32 v201, 0xffff0000, v122
	v_lshlrev_b32_e32 v202, 16, v123
	v_and_b32_e32 v203, 0xffff0000, v123
	v_lshlrev_b32_e32 v204, 16, v124
	v_and_b32_e32 v205, 0xffff0000, v124
	v_lshlrev_b32_e32 v206, 16, v125
	v_and_b32_e32 v207, 0xffff0000, v125
	v_pk_fma_f32 v[26:27], v[26:27], s[40:41], v[200:201]
	v_pk_fma_f32 v[28:29], v[28:29], s[40:41], v[202:203]
	v_pk_fma_f32 v[18:19], v[18:19], s[40:41], v[204:205]
	v_pk_fma_f32 v[20:21], v[20:21], s[40:41], v[206:207]
	v_cvt_pk_bf16_f32 v122, v26, v27
	v_cvt_pk_bf16_f32 v123, v28, v29
	v_cvt_pk_bf16_f32 v124, v18, v19
	v_cvt_pk_bf16_f32 v125, v20, v21
	v_pk_fma_f32 v[208:209], v[26:27], v[26:27], v[208:209]
	v_pk_fma_f32 v[208:209], v[28:29], v[28:29], v[208:209]
	v_pk_fma_f32 v[208:209], v[18:19], v[18:19], v[208:209]
	v_pk_fma_f32 v[208:209], v[20:21], v[20:21], v[208:209]
	global_store_dwordx4 v131, v[122:125], s[12:13] offset:256
	v_add_f32_e32 v212, v208, v209
	s_waitcnt vmcnt(12)
; __device__ __forceinline__ unsigned pk2(float lo, float hi) { f32x2 v = {lo, hi}; bf16x2_t b = __builtin_convertvector(v, bf16x2_t); return __builtin_bit_cast(unsigned, b); }
; __device__ __forceinline__ f32x4 bf_lo4(const u32x4& w) { return (f32x4){__uint_as_float(w[0] << 16), __uint_as_float(w[0] & 0xffff0000u), __uint_as_float(w[1] << 16), __uint_as_float(w[1] & 0xffff0000u)}; }
; __device__ __forceinline__ f32x4 bf_hi4(const u32x4& w) { return (f32x4){__uint_as_float(w[2] << 16), __uint_as_float(w[2] & 0xffff0000u), __uint_as_float(w[3] << 16), __uint_as_float(w[3] & 0xffff0000u)}; }
; __device__ __forceinline__ void epi_resid(bf16_t* XB, float* SS, float alpha, const f32x4 (&acc)[2][2][4][2], const Unit& u, int wr, int wc, int fr, int fq) {
;     ...
;         for (int bj = 0; bj < 2; ++bj) {
;             const size_t off = (size_t)r * DM + c0 + bj * 128;
;             const u32x4 bw = pre[it & 1][bj];
;             const f32x4 o0 = bf_lo4(bw) + acc[ai][bj][m][0] * alpha, o1 = bf_hi4(bw) + acc[ai][bj][m][1] * alpha;
;             u32x4 w; w[0] = pk2(o0[0], o0[1]); w[1] = pk2(o0[2], o0[3]); w[2] = pk2(o1[0], o1[1]); w[3] = pk2(o1[2], o1[3]);
;             *(u32x4*)(XB + off) = w;
;             q += (o0[0] * o0[0] + o0[1] * o0[1]) + (o0[2] * o0[2] + o0[3] * o0[3]) + (o1[0] * o1[0] + o1[1] * o1[1]) + (o1[2] * o1[2] + o1[3] * o1[3]);
;         }
;         q += __shfl_xor(q, 16); q += __shfl_xor(q, 32);
;         if (fq == 0) SS[(size_t)r * 32 + u.pn * 4 + wc] = q;
;         asm volatile("" ::: "memory");
;     }
	v_lshlrev_b32_e32 v200, 16, v118
	v_and_b32_e32 v201, 0xffff0000, v118
	v_lshlrev_b32_e32 v202, 16, v119
	v_and_b32_e32 v203, 0xffff0000, v119
	v_lshlrev_b32_e32 v204, 16, v120
	v_and_b32_e32 v205, 0xffff0000, v120
	v_lshlrev_b32_e32 v206, 16, v121
	v_and_b32_e32 v207, 0xffff0000, v121
	v_pk_fma_f32 v[14:15], v[14:15], s[40:41], v[200:201]
	v_pk_fma_f32 v[16:17], v[16:17], s[40:41], v[202:203]
	v_pk_fma_f32 v[6:7], v[6:7], s[40:41], v[204:205]
	v_pk_fma_f32 v[8:9], v[8:9], s[40:41], v[206:207]
	v_cvt_pk_bf16_f32 v118, v14, v15
	v_cvt_pk_bf16_f32 v119, v16, v17
	v_cvt_pk_bf16_f32 v120, v6, v7
	v_cvt_pk_bf16_f32 v121, v8, v9
	v_pk_mul_f32 v[208:209], v[14:15], v[14:15]
	v_pk_fma_f32 v[208:209], v[16:17], v[16:17], v[208:209]
	v_pk_fma_f32 v[208:209], v[6:7], v[6:7], v[208:209]
	v_pk_fma_f32 v[208:209], v[8:9], v[8:9], v[208:209]
	v_add_u32_e32 v131, 0xb0000, v130
	global_store_dwordx4 v131, v[118:121], s[12:13]
	v_lshlrev_b32_e32 v200, 16, v114
	v_and_b32_e32 v201, 0xffff0000, v114
	v_lshlrev_b32_e32 v202, 16, v115
	v_and_b32_e32 v203, 0xffff0000, v115
	v_lshlrev_b32_e32 v204, 16, v116
	v_and_b32_e32 v205, 0xffff0000, v116
	v_lshlrev_b32_e32 v206, 16, v117
	v_and_b32_e32 v207, 0xffff0000, v117
	v_pk_fma_f32 v[10:11], v[10:11], s[40:41], v[200:201]
	v_pk_fma_f32 v[12:13], v[12:13], s[40:41], v[202:203]
	v_pk_fma_f32 v[2:3], v[2:3], s[40:41], v[204:205]
	v_pk_fma_f32 v[4:5], v[4:5], s[40:41], v[206:207]
	v_cvt_pk_bf16_f32 v114, v10, v11
	v_cvt_pk_bf16_f32 v115, v12, v13
	v_cvt_pk_bf16_f32 v116, v2, v3
	v_cvt_pk_bf16_f32 v117, v4, v5
	v_pk_fma_f32 v[208:209], v[10:11], v[10:11], v[208:209]
	v_pk_fma_f32 v[208:209], v[12:13], v[12:13], v[208:209]
	v_pk_fma_f32 v[208:209], v[2:3], v[2:3], v[208:209]
	v_pk_fma_f32 v[208:209], v[4:5], v[4:5], v[208:209]
	global_store_dwordx4 v131, v[114:117], s[12:13] offset:256
	v_add_f32_e32 v213, v208, v209
	ds_bpermute_b32 v200, v214, v244
	ds_bpermute_b32 v201, v214, v245
	ds_bpermute_b32 v202, v214, v246
	ds_bpermute_b32 v203, v214, v247
	ds_bpermute_b32 v204, v214, v210
	ds_bpermute_b32 v205, v214, v211
	ds_bpermute_b32 v206, v214, v212
	ds_bpermute_b32 v207, v214, v213
	s_waitcnt lgkmcnt(0)
	v_add_f32_e32 v244, v244, v200
	v_add_f32_e32 v245, v245, v201
	v_add_f32_e32 v246, v246, v202
	v_add_f32_e32 v247, v247, v203
	v_add_f32_e32 v210, v210, v204
	v_add_f32_e32 v211, v211, v205
	v_add_f32_e32 v212, v212, v206
	v_add_f32_e32 v213, v213, v207
	ds_bpermute_b32 v200, v215, v244
	ds_bpermute_b32 v201, v215, v245
	ds_bpermute_b32 v202, v215, v246
	ds_bpermute_b32 v203, v215, v247
	ds_bpermute_b32 v204, v215, v210
	ds_bpermute_b32 v205, v215, v211
	ds_bpermute_b32 v206, v215, v212
	ds_bpermute_b32 v207, v215, v213
	s_waitcnt lgkmcnt(0)
	v_add_f32_e32 v244, v244, v200
	v_add_f32_e32 v245, v245, v201
	v_add_f32_e32 v246, v246, v202
	v_add_f32_e32 v247, v247, v203
	v_add_f32_e32 v210, v210, v204
	v_add_f32_e32 v211, v211, v205
	v_add_f32_e32 v212, v212, v206
	v_add_f32_e32 v213, v213, v207
	s_and_saveexec_b64 s[14:15], s[8:9]
	global_store_dword v180, v244, s[2:3] offset:-4096
	global_store_dword v180, v245, s[2:3] offset:-2048
	global_store_dword v180, v246, s[2:3]
	global_store_dword v180, v247, s[2:3] offset:2048
	global_store_dword v181, v210, s[2:3] offset:-4096
	global_store_dword v181, v211, s[2:3] offset:-2048
	global_store_dword v181, v212, s[2:3]
	global_store_dword v181, v213, s[2:3] offset:2048
	s_or_b64 exec, exec, s[14:15]
	s_mov_b64 s[2:3], 0
